# NA tile loop: straight-line fast path for the ring loader in neighbourhood mode (skips the wave-uniform mode switch, 2 calls per step)
# speedup vs baseline: 1.0073x; 1.0015x over previous
.LBB0_499:
	s_bitcmp1_b32 s56, 0
	s_cselect_b64 s[0:1], -1, 0
	s_mov_b32 s24, 1
	s_and_b64 vcc, exec, s[0:1]
	s_cbranch_vccnz .LBB0_532
	s_cmp_eq_u32 s52, 3
	s_cbranch_scc0 .Lna_ld1_slow
	s_ashr_i32 s0, s60, 1
	s_mul_hi_i32 s1, s0, 0xe0000
	s_mul_i32 s0, s0, 0xe0000
	s_add_u32 s0, s86, s0
	s_addc_u32 s1, s87, s1
	s_bfe_i32 s10, s60, 0x10000
	s_and_b32 s10, s10, s98
	s_add_u32 s0, s0, s10
	s_addc_u32 s1, s1, 0
	s_lshl_b32 s10, s57, 14
	s_add_i32 s10, s30, s10
	s_mov_b32 m0, s10
	s_nop 0
	global_load_lds_dwordx4 v182, s[0:1]
	s_add_i32 m0, s10, 0x400
	s_nop 0
	global_load_lds_dwordx4 v171, s[0:1]
	s_add_i32 s0, s57, 1
	s_cmp_lg_u32 s0, 6
	s_cselect_b32 s57, s0, 0
	s_add_i32 s60, s60, 1
	s_cmp_lg_u32 s60, s70
	s_mov_b32 s24, 0
	s_cbranch_scc1 .LBB0_532
	s_branch .Lna_ld1_trans
.Lna_ld1_slow:
	s_cmp_lt_i32 s52, 2
	s_cbranch_scc1 .LBB0_503
	s_cmp_gt_i32 s52, 2
	s_cbranch_scc0 .LBB0_504
	s_cmp_lg_u32 s52, 3
	s_mov_b64 s[10:11], -1
	s_cselect_b64 s[0:1], -1, 0
	s_cbranch_execz .LBB0_505
	s_branch .LBB0_506

.Lna_ld1_trans:
	s_add_i32 s0, s55, s82
	s_add_i32 s54, s54, s42
	s_add_i32 s1, s0, -3
	s_cmp_gt_i32 s0, 2
	s_cselect_b32 s0, s1, s0
	s_cmp_eq_u32 s0, 1
	s_cselect_b32 s1, s83, 0x600
	s_cmp_lg_u32 s0, 0
	s_cselect_b32 s10, s1, 0x300
	s_cmp_gt_i32 s55, 1
	s_cselect_b64 s[0:1], -1, 0
	s_cmp_ge_i32 s54, s10
	s_cselect_b64 s[10:11], -1, 0
	s_and_b64 s[12:13], s[10:11], exec
	s_cselect_b32 s54, s66, s54
	s_and_b64 s[0:1], s[10:11], s[0:1]
	s_cmp_lg_u64 s[10:11], 0
	s_addc_u32 s55, s55, 0
	s_mov_b32 s24, 1
	s_and_b64 vcc, exec, s[0:1]
	s_cbranch_vccnz .LBB0_531
	s_add_i32 s0, s55, s82
	s_add_i32 s1, s0, -3
	s_cmp_gt_i32 s0, 2
	s_cselect_b32 s0, s1, s0
	s_cmp_eq_u32 s0, 1
	s_cselect_b32 s1, 1, 2
	s_cmp_lg_u32 s0, 0
	s_cselect_b32 s0, s1, 0
	s_cmp_lt_i32 s0, 1
	s_cbranch_scc1 .LBB0_528
	s_cmp_lg_u32 s0, 1
	s_mov_b64 s[0:1], -1
	s_cbranch_scc0 .LBB0_525
	s_mul_hi_i32 s0, s54, 0x2aaaaaab
	s_lshr_b32 s1, s0, 31
	s_ashr_i32 s0, s0, 7
	s_add_i32 s0, s0, s1
	s_add_i32 s24, s0, 1
	s_mulk_i32 s0, 0x300
	s_sub_i32 s0, s54, s0
	s_mul_i32 s1, s0, 0x2aab
	s_lshr_b32 s4, s1, 31
	s_ashr_i32 s1, s1, 19
	s_add_i32 s1, s1, s4
	s_mul_i32 s4, s1, 48
	s_sub_i32 s0, s0, s4
	s_sext_i32_i16 s25, s0
	s_and_b32 s13, s25, 7
	s_mul_hi_i32 s0, s1, 0x1c00000
	s_mul_i32 s1, s1, 0x1c00000
	s_add_u32 s4, s96, s1
	s_addc_u32 s5, s97, s0
	s_lshl_b32 s0, s25, 4
	s_and_b32 s0, s0, 0xffffff80
	s_add_i32 s98, s0, 0xf00
	s_lshl_b64 s[0:1], s[98:99], 1
	s_add_u32 s14, s4, s0
	s_addc_u32 s15, s5, s1
	s_cmp_lg_u32 s24, 2
	s_mov_b64 s[0:1], -1
	s_cbranch_scc0 .LBB0_522
	s_cmp_eq_u32 s24, 0
	s_cselect_b64 s[0:1], -1, 0
	s_add_i32 s4, s54, 0x2ff
	s_lshr_b32 s5, s13, 1
	s_and_b32 s10, s25, 1
	s_cmpk_lt_u32 s4, 0x5ff
	s_mulk_i32 s5, 0x3800
	s_cselect_b32 s4, s5, 0
	s_cselect_b32 s5, s10, s13
	s_lshl_b32 s10, s5, 8
	s_and_b64 s[0:1], s[0:1], exec
	s_movk_i32 s0, 0x800
	s_cselect_b32 s11, s0, 0x200
	s_mov_b32 s0, 0xe000
	s_cselect_b32 s98, 0x3800, s0
	s_add_u32 s86, s14, s4
	s_addc_u32 s87, s15, 0
	s_mov_b64 s[0:1], 0
	s_mov_b32 s12, s98
	s_mov_b64 s[4:5], s[98:99]

.LBB0_532:
	s_bitcmp1_b32 s24, 0
	s_cselect_b64 s[0:1], -1, 0
	s_mov_b32 s10, 1
	s_and_b64 vcc, exec, s[0:1]
	s_cbranch_vccnz .LBB0_565
	s_cmp_eq_u32 s52, 3
	s_cbranch_scc0 .Lna_ld2_slow
	s_ashr_i32 s0, s60, 1
	s_mul_hi_i32 s1, s0, 0xe0000
	s_mul_i32 s0, s0, 0xe0000
	s_add_u32 s0, s86, s0
	s_addc_u32 s1, s87, s1
	s_bfe_i32 s10, s60, 0x10000
	s_and_b32 s10, s10, s98
	s_add_u32 s0, s0, s10
	s_addc_u32 s1, s1, 0
	s_lshl_b32 s10, s57, 14
	s_add_i32 s10, s30, s10
	s_mov_b32 m0, s10
	s_nop 0
	global_load_lds_dwordx4 v182, s[0:1]
	s_add_i32 m0, s10, 0x400
	s_nop 0
	global_load_lds_dwordx4 v171, s[0:1]
	s_add_i32 s0, s57, 1
	s_cmp_lg_u32 s0, 6
	s_cselect_b32 s57, s0, 0
	s_add_i32 s60, s60, 1
	s_cmp_lg_u32 s60, s70
	s_mov_b32 s10, 0
	s_cbranch_scc1 .LBB0_565
	s_branch .Lna_ld2_trans

.Lna_ld2_trans:
	s_add_i32 s0, s55, s82
	s_add_i32 s14, s54, s42
	s_add_i32 s1, s0, -3
	s_cmp_gt_i32 s0, 2
	s_cselect_b32 s0, s1, s0
	s_cmp_eq_u32 s0, 1
	s_cselect_b32 s1, s83, 0x600
	s_cmp_lg_u32 s0, 0
	s_cselect_b32 s10, s1, 0x300
	s_cmp_gt_i32 s55, 1
	s_cselect_b64 s[0:1], -1, 0
	s_cmp_ge_i32 s14, s10
	s_cselect_b64 s[10:11], -1, 0
	s_and_b64 s[12:13], s[10:11], exec
	s_cselect_b32 s54, s66, s14
	s_cmp_lg_u64 s[10:11], 0
	s_addc_u32 s55, s55, 0
	s_and_b64 s[0:1], s[10:11], s[0:1]
	s_mov_b32 s10, 1
	s_and_b64 vcc, exec, s[0:1]
	s_cbranch_vccnz .LBB0_564
	s_add_i32 s0, s55, s82
	s_add_i32 s1, s0, -3
	s_cmp_gt_i32 s0, 2
	s_cselect_b32 s0, s1, s0
	s_cmp_eq_u32 s0, 1
	s_cselect_b32 s1, 1, 2
	s_cmp_lg_u32 s0, 0
	s_cselect_b32 s0, s1, 0
	s_cmp_lt_i32 s0, 1
	s_cbranch_scc1 .LBB0_561
	s_cmp_lg_u32 s0, 1
	s_mov_b64 s[0:1], -1
	s_cbranch_scc0 .LBB0_558
	s_mul_hi_i32 s0, s54, 0x2aaaaaab
	s_lshr_b32 s1, s0, 31
	s_ashr_i32 s0, s0, 7
	s_add_i32 s0, s0, s1
	s_add_i32 s25, s0, 1
	s_mulk_i32 s0, 0x300
	s_sub_i32 s0, s54, s0
	s_mul_i32 s1, s0, 0x2aab
	s_lshr_b32 s4, s1, 31
	s_ashr_i32 s1, s1, 19
	s_add_i32 s1, s1, s4
	s_mul_i32 s4, s1, 48
	s_sub_i32 s0, s0, s4
	s_sext_i32_i16 s26, s0
	s_and_b32 s13, s26, 7
	s_mul_hi_i32 s0, s1, 0x1c00000
	s_mul_i32 s1, s1, 0x1c00000
	s_add_u32 s4, s96, s1
	s_addc_u32 s5, s97, s0
	s_lshl_b32 s0, s26, 4
	s_and_b32 s0, s0, 0xffffff80
	s_add_i32 s98, s0, 0xf00
	s_lshl_b64 s[0:1], s[98:99], 1
	s_add_u32 s14, s4, s0
	s_addc_u32 s15, s5, s1
	s_cmp_lg_u32 s25, 2
	s_mov_b64 s[0:1], -1
	s_cbranch_scc0 .LBB0_555
	s_cmp_eq_u32 s25, 0
	s_cselect_b64 s[0:1], -1, 0
	s_add_i32 s4, s54, 0x2ff
	s_lshr_b32 s5, s13, 1
	s_and_b32 s10, s26, 1
	s_cmpk_lt_u32 s4, 0x5ff
	s_mulk_i32 s5, 0x3800
	s_cselect_b32 s4, s5, 0
	s_cselect_b32 s5, s10, s13
	s_lshl_b32 s11, s5, 8
	s_and_b64 s[0:1], s[0:1], exec
	s_movk_i32 s0, 0x800
	s_cselect_b32 s12, s0, 0x200
	s_mov_b32 s0, 0xe000
	s_cselect_b32 s98, 0x3800, s0
	s_add_u32 s86, s14, s4
	s_addc_u32 s87, s15, 0
	s_mov_b64 s[0:1], 0
	s_mov_b32 s10, s98
	s_mov_b64 s[4:5], s[98:99]
